# three-class wave-spread deal of the prep transposes (A 800, B 1740, C 3220 items)
# speedup vs baseline: 1.0009x; 1.0009x over previous
.LBB0_87:
	s_and_b64 s[0:1], s[0:1], s[8:9]
	s_movk_i32 s2, 0x700
	s_and_b64 s[0:1], s[0:1], exec
	s_cselect_b32 s8, s2, 0x1680
	v_readlane_b32 s0, v251, 46
	s_cmpk_lt_i32 s63, 0x80
	s_cbranch_scc1 .Ldeal_ab
	s_lshl_b32 s0, s0, 7
	s_add_i32 s0, s0, s63
	s_add_i32 s6, s0, 0xffffff80
	s_movk_i32 s7, 0x400
	s_movk_i32 s8, 0xc94
	s_branch .Ldeal_done
.Ldeal_ab:
	s_lshl_b32 s0, s0, 6
	s_add_i32 s0, s0, s63
	s_movk_i32 s7, 0x200
	s_cmpk_lt_i32 s63, 0x40
	s_cbranch_scc1 .Ldeal_a
	s_add_i32 s6, s0, 0xc54
	s_movk_i32 s8, 0x1360
	s_branch .Ldeal_done
.Ldeal_a:
	s_add_i32 s6, s0, 0x1360
	s_movk_i32 s8, 0x1680
.Ldeal_done:
	s_cmp_ge_i32 s6, s8
	s_cbranch_scc1 .LBB0_102
	v_readlane_b32 s0, v251, 46
	v_lshlrev_b32_e32 v0, 2, v81
	s_mulk_i32 s0, 0x4100
	v_lshrrev_b32_e32 v4, 4, v81
	v_and_b32_e32 v0, 60, v0
	s_add_i32 s0, s0, 0
	v_lshlrev_b32_e32 v2, 2, v0
	v_mul_u32_u24_e32 v3, 0x104, v4
	v_add3_u32 v5, s0, v2, v3
	v_lshlrev_b32_e32 v2, 3, v81
	s_movk_i32 s1, 0x104
	v_and_b32_e32 v2, 56, v2
	v_mov_b32_e32 v3, s0
	v_lshrrev_b32_e32 v6, 3, v81
	v_mad_u32_u24 v7, v2, s1, v3
	v_bfe_u32 v3, v81, 3, 2
	v_lshl_add_u32 v8, v6, 2, v7
	v_and_or_b32 v12, v85, 8, v3
	s_mov_b32 s3, 0
	v_mov_b32_e32 v1, 0
	v_or_b32_e32 v9, 8, v6
	v_or_b32_e32 v10, 16, v6
	v_or_b32_e32 v11, 24, v6
	v_or_b32_e32 v13, 4, v12
	v_or_b32_e32 v14, 16, v12
	v_or_b32_e32 v15, 20, v12
	s_lshl_b32 s9, s6, 6
	s_lshl_b32 s10, s7, 6
	s_lshl_b32 s11, s6, 2
	s_lshl_b32 s12, s7, 2
	s_movk_i32 s13, 0x4000
	s_mov_b32 s14, 0x8000
	s_mov_b32 s15, 0xc000
	s_mov_b32 s16, 0x10000
	s_mov_b32 s17, 0x14000
	s_mov_b32 s18, 0x18000
	s_mov_b32 s19, 0x1c000
	s_mov_b32 s20, 0x20000
	s_mov_b32 s21, 0x24000
	s_mov_b32 s22, 0x28000
	s_mov_b32 s23, 0x2c000
	s_mov_b32 s24, 0x30000
	s_mov_b32 s26, 0x34000
	s_mov_b32 s27, 0x38000
	s_mov_b32 s28, 0x3c000
	v_add_u32_e32 v16, 0x410, v5
	v_add_u32_e32 v17, 0x418, v5
	v_add_u32_e32 v18, 0x820, v5
	v_add_u32_e32 v19, 0x828, v5
	v_add_u32_e32 v20, 0xc30, v5
	v_add_u32_e32 v21, 0xc38, v5
	v_add_u32_e32 v22, 0x1040, v5
	v_add_u32_e32 v23, 0x1048, v5
	v_add_u32_e32 v24, 0x1450, v5
	v_add_u32_e32 v25, 0x1458, v5
	v_add_u32_e32 v26, 0x1860, v5
	v_add_u32_e32 v27, 0x1868, v5
	v_add_u32_e32 v28, 0x1c70, v5
	v_add_u32_e32 v29, 0x1c78, v5
	v_add_u32_e32 v30, 0x2080, v5
	v_add_u32_e32 v31, 0x2088, v5
	v_add_u32_e32 v32, 0x2490, v5
	v_add_u32_e32 v33, 0x2498, v5
	v_add_u32_e32 v34, 0x28a0, v5
	v_add_u32_e32 v35, 0x28a8, v5
	v_add_u32_e32 v36, 0x2cb0, v5
	v_add_u32_e32 v37, 0x2cb8, v5
	v_add_u32_e32 v38, 0x30c0, v5
	v_add_u32_e32 v39, 0x30c8, v5
	v_add_u32_e32 v40, 0x34d0, v5
	v_add_u32_e32 v41, 0x34d8, v5
	v_add_u32_e32 v42, 0x38e0, v5
	v_add_u32_e32 v43, 0x38e8, v5
	v_add_u32_e32 v44, 0x3cf0, v5
	v_add_u32_e32 v45, 0x3cf8, v5
	s_mov_b32 s29, 0x6e000
	s_mov_b32 s30, 0x32000
	s_mov_b32 s31, 0x46000
	s_mov_b32 s34, 0x50000
	s_mov_b32 s35, 0x5a000
	s_mov_b32 s36, 0x64000
	s_mov_b32 s37, 0x78000
	s_mov_b32 s38, 0x82000
	s_mov_b32 s39, 0x8c000
	s_mov_b32 s40, 0x96000
	v_lshlrev_b32_e32 v0, 2, v0
	v_lshlrev_b32_e32 v2, 1, v2
	v_add_u32_e32 v46, 0x400, v8
	s_branch .LBB0_90
